# v52: v41 + grid-barrier leader does release first (wbl2, wait, TOP atomic) and issues its acquire buffer_inv after the TOP atomic so it overlaps the TOP poll
# speedup vs baseline: 1.0119x; 1.0010x over previous
.LBB0_334:
	s_andn2_saveexec_b64 s[6:7], s[6:7]
	s_cbranch_execz .LBB0_352
	s_mov_b64 s[6:7], exec
	buffer_wbl2 sc1
	v_add_u32_e32 v3, 1, v3
	v_mul_lo_u32 v3, v3, v2
	v_mov_b32_e32 v4, 0x1ac3000
	v_mov_b32_e32 v5, 1
	s_waitcnt vmcnt(0) lgkmcnt(0)
	global_atomic_add v4, v5, s[46:47] offset:1024
	buffer_inv sc1

.LBB0_1453:
	s_andn2_saveexec_b64 s[10:11], s[10:11]
	s_cbranch_execz .LBB0_1471
	s_mov_b64 s[10:11], exec
	buffer_wbl2 sc1
	v_add_u32_e32 v3, 1, v3
	v_mul_lo_u32 v3, v3, v2
	v_mov_b32_e32 v4, 0x1ac3000
	v_mov_b32_e32 v5, 1
	s_waitcnt vmcnt(0) lgkmcnt(0)
	global_atomic_add v4, v5, s[46:47] offset:1024
	buffer_inv sc1

.LBB0_1737:
	s_andn2_saveexec_b64 s[8:9], s[8:9]
	s_cbranch_execz .LBB0_1755
	s_mov_b64 s[8:9], exec
	buffer_wbl2 sc1
	v_add_u32_e32 v19, 1, v19
	v_mul_lo_u32 v19, v19, v18
	v_mov_b32_e32 v20, 0x1ac3000
	v_mov_b32_e32 v21, 1
	s_waitcnt vmcnt(0) lgkmcnt(0)
	global_atomic_add v20, v21, s[46:47] offset:1024
	buffer_inv sc1

.LBB0_1821:
	s_andn2_saveexec_b64 s[6:7], s[6:7]
	s_cbranch_execz .LBB0_1839
	s_mov_b64 s[6:7], exec
	buffer_wbl2 sc1
	v_add_u32_e32 v1, 1, v1
	v_mul_lo_u32 v1, v1, v0
	v_mov_b32_e32 v2, 0x1ac3000
	v_mov_b32_e32 v3, 1
	s_waitcnt vmcnt(0) lgkmcnt(0)
	global_atomic_add v2, v3, s[46:47] offset:1024
	buffer_inv sc1
